# DA tile loop: softmax row-sum of each tile deferred into the P.V MFMA shadow of the next MFMA block (block order PV g1-g3, QK, PV g4); on top of waits+prio+rotation
# speedup vs baseline: 1.0102x; 1.0052x over previous
.LBB0_598:
	v_add_f32_e32 v184, v18, v19
	v_lshlrev_b32_e32 v18, 1, v50
	v_and_b32_e32 v18, 32, v18
	v_and_or_b32 v18, v51, s66, v18
	v_and_b32_e32 v19, 0x100, v52
	v_fmac_f32_e32 v184, 0, v56
	v_or3_b32 v187, v18, v19, v53
	s_add_i32 s35, 0, 0xc000
	v_cmp_gt_u32_e64 s[4:5], 32, v50
	v_lshl_add_u32 v186, v54, 2, s18
	v_lshlrev_b32_e32 v185, 4, v55
	v_mov_b64_e32 v[32:33], v[16:17]
	v_mov_b64_e32 v[48:49], v[16:17]
	v_mov_b64_e32 v[64:65], v[16:17]
	s_mov_b32 s96, 1
	v_add_u32_e32 v193, s35, v187
	s_lshl_b32 s97, s12, 8
	s_mov_b32 s12, 0x8000
	s_movk_i32 s74, 0x4000
	s_mov_b32 s0, 0
	v_mov_b64_e32 v[30:31], v[14:15]
	v_mov_b64_e32 v[28:29], v[12:13]
	v_mov_b64_e32 v[26:27], v[10:11]
	v_mov_b64_e32 v[24:25], v[8:9]
	v_mov_b64_e32 v[22:23], v[6:7]
	v_mov_b64_e32 v[20:21], v[4:5]
	v_mov_b64_e32 v[18:19], v[2:3]
	v_mov_b64_e32 v[46:47], v[14:15]
	v_mov_b64_e32 v[44:45], v[12:13]
	v_mov_b64_e32 v[42:43], v[10:11]
	v_mov_b64_e32 v[40:41], v[8:9]
	v_mov_b64_e32 v[38:39], v[6:7]
	v_mov_b64_e32 v[36:37], v[4:5]
	v_mov_b64_e32 v[34:35], v[2:3]
	v_mov_b64_e32 v[62:63], v[14:15]
	v_mov_b64_e32 v[60:61], v[12:13]
	v_mov_b64_e32 v[58:59], v[10:11]
	v_mov_b64_e32 v[56:57], v[8:9]
	v_mov_b64_e32 v[54:55], v[6:7]
	v_mov_b64_e32 v[52:53], v[4:5]
	v_mov_b64_e32 v[50:51], v[2:3]
	s_mov_b32 s75, s74
	s_mov_b32 s74, s0
	v_add_u32_e32 v238, s74, v193
	v_mov_b32_e32 v244, 1.0
	v_mov_b32_e32 v82, 0
	v_mov_b32_e32 v83, 0
	v_mov_b32_e32 v84, 0
	v_mov_b32_e32 v85, 0
	v_mov_b32_e32 v86, 0
	v_mov_b32_e32 v87, 0
	v_mov_b32_e32 v88, 0
	v_mov_b32_e32 v89, 0
	v_mov_b32_e32 v90, 0
	v_mov_b32_e32 v91, 0
	v_mov_b32_e32 v92, 0
	v_mov_b32_e32 v93, 0
	v_mov_b32_e32 v94, 0
	v_mov_b32_e32 v95, 0
	v_mov_b32_e32 v96, 0
	v_mov_b32_e32 v97, 0
	v_mov_b32_e32 v98, 0
	v_mov_b32_e32 v99, 0
	v_mov_b32_e32 v100, 0
	v_mov_b32_e32 v101, 0
	v_mov_b32_e32 v102, 0
	v_mov_b32_e32 v103, 0
	v_mov_b32_e32 v104, 0
	v_mov_b32_e32 v105, 0
	v_mov_b32_e32 v106, 0
	v_mov_b32_e32 v107, 0
	v_mov_b32_e32 v108, 0
	v_mov_b32_e32 v109, 0
	v_mov_b32_e32 v110, 0
	v_mov_b32_e32 v111, 0
	v_mov_b32_e32 v112, 0
	v_mov_b32_e32 v113, 0
.LBB0_599:
	s_barrier
	s_setprio 3
	ds_read_b64_tr_b16 v[194:195], v238 offset:0
	ds_read_b64_tr_b16 v[196:197], v238 offset:0x800
	ds_read_b64_tr_b16 v[198:199], v238 offset:0x1000
	ds_read_b64_tr_b16 v[200:201], v238 offset:0x1800
	ds_read_b64_tr_b16 v[202:203], v238 offset:0x2000
	ds_read_b64_tr_b16 v[204:205], v238 offset:0x2800
	ds_read_b64_tr_b16 v[206:207], v238 offset:0x3000
	ds_read_b64_tr_b16 v[208:209], v238 offset:0x3800
	ds_read_b128 v[226:229], v188 offset:45056
	ds_read_b128 v[230:233], v189 offset:40960
	ds_read_b128 v[234:237], v189 offset:45056
	s_waitcnt lgkmcnt(9)
	v_mfma_f32_32x32x16_bf16 v[50:65], v[142:145], v[194:197], v[50:65]
	v_add_f32_e32 v242, v82, v83
	v_add_f32_e32 v242, v84, v242
	v_add_f32_e32 v242, v85, v242
	ds_read_b64_tr_b16 v[210:211], v238 offset:0x200
	ds_read_b64_tr_b16 v[212:213], v238 offset:0xa00
	s_waitcnt lgkmcnt(9)
	v_mfma_f32_32x32x16_bf16 v[50:65], v[138:141], v[198:201], v[50:65]
	v_add_f32_e32 v242, v86, v242
	v_add_f32_e32 v242, v87, v242
	v_add_f32_e32 v242, v88, v242
	ds_read_b64_tr_b16 v[214:215], v238 offset:0x1200
	ds_read_b64_tr_b16 v[216:217], v238 offset:0x1a00
	s_waitcnt lgkmcnt(9)
	v_mfma_f32_32x32x16_bf16 v[50:65], v[134:137], v[202:205], v[50:65]
	v_add_f32_e32 v242, v89, v242
	v_add_f32_e32 v242, v90, v242
	v_add_f32_e32 v242, v91, v242
	ds_read_b64_tr_b16 v[218:219], v238 offset:0x2200
	ds_read_b64_tr_b16 v[220:221], v238 offset:0x2a00
	s_waitcnt lgkmcnt(9)
	v_mfma_f32_32x32x16_bf16 v[50:65], v[130:133], v[206:209], v[50:65]
	v_add_f32_e32 v242, v92, v242
	v_add_f32_e32 v242, v93, v242
	v_add_f32_e32 v242, v94, v242
	ds_read_b64_tr_b16 v[222:223], v238 offset:0x3200
	ds_read_b64_tr_b16 v[224:225], v238 offset:0x3a00
	s_waitcnt lgkmcnt(6)
	v_mfma_f32_32x32x16_bf16 v[34:49], v[142:145], v[210:213], v[34:49]
	v_add_f32_e32 v242, v95, v242
	v_add_f32_e32 v242, v96, v242
	v_add_f32_e32 v242, v97, v242
	ds_read_b64_tr_b16 v[194:195], v238 offset:0x400
	ds_read_b64_tr_b16 v[196:197], v238 offset:0xc00
	ds_read_b128 v[82:85], v188 offset:40960
	s_waitcnt lgkmcnt(7)
	v_mfma_f32_32x32x16_bf16 v[34:49], v[138:141], v[214:217], v[34:49]
	v_add_f32_e32 v242, v98, v242
	v_add_f32_e32 v242, v99, v242
	v_add_f32_e32 v242, v100, v242
	ds_read_b64_tr_b16 v[198:199], v238 offset:0x1400
	ds_read_b64_tr_b16 v[200:201], v238 offset:0x1c00
	s_waitcnt lgkmcnt(7)
	v_mfma_f32_32x32x16_bf16 v[34:49], v[134:137], v[218:221], v[34:49]
	v_add_f32_e32 v242, v101, v242
	v_add_f32_e32 v242, v102, v242
	v_add_f32_e32 v242, v103, v242
	ds_read_b64_tr_b16 v[202:203], v238 offset:0x2400
	ds_read_b64_tr_b16 v[204:205], v238 offset:0x2c00
	s_waitcnt lgkmcnt(7)
	v_mfma_f32_32x32x16_bf16 v[34:49], v[130:133], v[222:225], v[34:49]
	v_add_f32_e32 v242, v104, v242
	v_add_f32_e32 v242, v105, v242
	v_add_f32_e32 v242, v106, v242
	ds_read_b64_tr_b16 v[206:207], v238 offset:0x3400
	ds_read_b64_tr_b16 v[208:209], v238 offset:0x3c00
	s_waitcnt lgkmcnt(7)
	v_mfma_f32_32x32x16_bf16 v[18:33], v[142:145], v[194:197], v[18:33]
	v_add_f32_e32 v242, v107, v242
	v_add_f32_e32 v242, v108, v242
	v_add_f32_e32 v242, v109, v242
	ds_read_b64_tr_b16 v[210:211], v238 offset:0x600
	ds_read_b64_tr_b16 v[212:213], v238 offset:0xe00
	s_waitcnt lgkmcnt(6)
	v_mfma_f32_32x32x16_bf16 v[18:33], v[138:141], v[198:201], v[18:33]
	v_add_f32_e32 v242, v110, v242
	v_add_f32_e32 v242, v111, v242
	v_add_f32_e32 v242, v112, v242
	ds_read_b64_tr_b16 v[214:215], v238 offset:0x1600
	ds_read_b64_tr_b16 v[216:217], v238 offset:0x1e00
	s_waitcnt lgkmcnt(6)
	v_mfma_f32_32x32x16_bf16 v[18:33], v[134:137], v[202:205], v[18:33]
	v_add_f32_e32 v242, v113, v242
	v_mov_b32_e32 v243, v242
	s_nop 1
	ds_read_b64_tr_b16 v[218:219], v238 offset:0x2600
	ds_read_b64_tr_b16 v[220:221], v238 offset:0x2e00
	s_waitcnt lgkmcnt(6)
	v_mfma_f32_32x32x16_bf16 v[18:33], v[130:133], v[206:209], v[18:33]
	v_permlane32_swap_b32_e32 v242, v243
	v_add_f32_e32 v242, v242, v243
	v_fmac_f32_e32 v242, v184, v244
	v_mov_b32_e32 v184, v242
	ds_read_b64_tr_b16 v[222:223], v238 offset:0x3600
	ds_read_b64_tr_b16 v[224:225], v238 offset:0x3e00
	ds_read_b128 v[194:197], v190 offset:40960
	ds_read_b128 v[198:201], v190 offset:45056
	ds_read_b128 v[202:205], v191 offset:40960
	ds_read_b128 v[206:209], v191 offset:45056
	v_mfma_f32_32x32x16_bf16 v[98:113], v[82:85], v[126:129], v[66:81]
	v_mfma_f32_32x32x16_bf16 v[82:97], v[226:229], v[126:129], v[66:81]
	v_mfma_f32_32x32x16_bf16 v[98:113], v[230:233], v[122:125], v[98:113]
	v_mfma_f32_32x32x16_bf16 v[82:97], v[234:237], v[122:125], v[82:97]
	s_waitcnt lgkmcnt(3)
	v_mfma_f32_32x32x16_bf16 v[98:113], v[194:197], v[118:121], v[98:113]
	s_waitcnt lgkmcnt(2)
	v_mfma_f32_32x32x16_bf16 v[82:97], v[198:201], v[118:121], v[82:97]
	s_waitcnt lgkmcnt(1)
	v_mfma_f32_32x32x16_bf16 v[98:113], v[202:205], v[114:117], v[98:113]
	s_waitcnt lgkmcnt(0)
	v_mfma_f32_32x32x16_bf16 v[82:97], v[206:209], v[114:117], v[82:97]
	v_mfma_f32_32x32x16_bf16 v[2:17], v[142:145], v[210:213], v[2:17]
	v_mfma_f32_32x32x16_bf16 v[2:17], v[138:141], v[214:217], v[2:17]
	v_mfma_f32_32x32x16_bf16 v[2:17], v[134:137], v[218:221], v[2:17]
	v_mfma_f32_32x32x16_bf16 v[2:17], v[130:133], v[222:225], v[2:17]
	s_and_b64 vcc, exec, s[6:7]
	s_cbranch_vccnz .LBB0_601
	s_waitcnt vmcnt(1)

.LBB0_610:
	v_exp_f32_e32 v98, v98
	v_exp_f32_e32 v99, v99
	v_exp_f32_e32 v100, v100
	v_exp_f32_e32 v101, v101
	v_exp_f32_e32 v102, v102
	v_exp_f32_e32 v103, v103
	v_exp_f32_e32 v104, v104
	v_exp_f32_e32 v105, v105
	v_exp_f32_e32 v106, v106
	v_exp_f32_e32 v107, v107
	v_exp_f32_e32 v108, v108
	v_exp_f32_e32 v109, v109
	v_exp_f32_e32 v110, v110
	v_exp_f32_e32 v111, v111
	v_exp_f32_e32 v112, v112
	v_exp_f32_e32 v113, v113
	v_exp_f32_e32 v82, v82
	v_exp_f32_e32 v83, v83
	v_exp_f32_e32 v84, v84
	v_exp_f32_e32 v85, v85
	v_exp_f32_e32 v86, v86
	v_exp_f32_e32 v87, v87
	v_exp_f32_e32 v88, v88
	v_exp_f32_e32 v89, v89
	v_exp_f32_e32 v90, v90
	v_exp_f32_e32 v91, v91
	v_exp_f32_e32 v92, v92
	v_exp_f32_e32 v93, v93
	v_exp_f32_e32 v94, v94
	v_exp_f32_e32 v95, v95
	v_exp_f32_e32 v96, v96
	v_exp_f32_e32 v97, v97
	s_and_b64 vcc, exec, s[2:3]
	v_cvt_pk_bf16_f32 v142, v98, v99
	v_cvt_pk_bf16_f32 v143, v100, v101
	v_cvt_pk_bf16_f32 v144, v102, v103
	v_cvt_pk_bf16_f32 v145, v104, v105
	v_cvt_pk_bf16_f32 v138, v106, v107
	v_cvt_pk_bf16_f32 v139, v108, v109
	v_cvt_pk_bf16_f32 v140, v110, v111
	v_cvt_pk_bf16_f32 v141, v112, v113
	v_cvt_pk_bf16_f32 v134, v82, v83
	v_cvt_pk_bf16_f32 v135, v84, v85
	v_cvt_pk_bf16_f32 v136, v86, v87
	v_cvt_pk_bf16_f32 v137, v88, v89
	v_cvt_pk_bf16_f32 v130, v90, v91
	v_cvt_pk_bf16_f32 v131, v92, v93
	v_cvt_pk_bf16_f32 v132, v94, v95
	v_cvt_pk_bf16_f32 v133, v96, v97
	s_cbranch_vccnz .LBB0_612
	s_waitcnt vmcnt(1)
.LBB0_612:
	s_barrier
	s_setprio 3
	v_add_u32_e32 v197, s75, v193
	ds_read_b64_tr_b16 v[198:199], v197 offset:0
	ds_read_b64_tr_b16 v[200:201], v197 offset:0x800
	ds_read_b64_tr_b16 v[202:203], v197 offset:0x1000
	ds_read_b64_tr_b16 v[204:205], v197 offset:0x1800
	ds_read_b64_tr_b16 v[206:207], v197 offset:0x2000
	ds_read_b64_tr_b16 v[208:209], v197 offset:0x2800
	ds_read_b64_tr_b16 v[210:211], v197 offset:0x3000
	ds_read_b64_tr_b16 v[212:213], v197 offset:0x3800
	ds_read_b128 v[230:233], v188 offset:36864
	ds_read_b128 v[234:237], v189 offset:32768
	ds_read_b128 v[238:241], v189 offset:36864
	s_waitcnt lgkmcnt(9)
	v_mfma_f32_32x32x16_bf16 v[50:65], v[142:145], v[198:201], v[50:65]
	v_add_f32_e32 v242, v82, v83
	v_add_f32_e32 v242, v84, v242
	v_add_f32_e32 v242, v85, v242
	ds_read_b64_tr_b16 v[214:215], v197 offset:0x200
	ds_read_b64_tr_b16 v[216:217], v197 offset:0xa00
	s_waitcnt lgkmcnt(9)
	v_mfma_f32_32x32x16_bf16 v[50:65], v[138:141], v[202:205], v[50:65]
	v_add_f32_e32 v242, v86, v242
	v_add_f32_e32 v242, v87, v242
	v_add_f32_e32 v242, v88, v242
	ds_read_b64_tr_b16 v[218:219], v197 offset:0x1200
	ds_read_b64_tr_b16 v[220:221], v197 offset:0x1a00
	s_waitcnt lgkmcnt(9)
	v_mfma_f32_32x32x16_bf16 v[50:65], v[134:137], v[206:209], v[50:65]
	v_add_f32_e32 v242, v89, v242
	v_add_f32_e32 v242, v90, v242
	v_add_f32_e32 v242, v91, v242
	ds_read_b64_tr_b16 v[222:223], v197 offset:0x2200
	ds_read_b64_tr_b16 v[224:225], v197 offset:0x2a00
	s_waitcnt lgkmcnt(9)
	v_mfma_f32_32x32x16_bf16 v[50:65], v[130:133], v[210:213], v[50:65]
	v_add_f32_e32 v242, v92, v242
	v_add_f32_e32 v242, v93, v242
	v_add_f32_e32 v242, v94, v242
	ds_read_b64_tr_b16 v[226:227], v197 offset:0x3200
	ds_read_b64_tr_b16 v[228:229], v197 offset:0x3a00
	s_waitcnt lgkmcnt(6)
	v_mfma_f32_32x32x16_bf16 v[34:49], v[142:145], v[214:217], v[34:49]
	v_add_f32_e32 v242, v95, v242
	v_add_f32_e32 v242, v96, v242
	v_add_f32_e32 v242, v97, v242
	ds_read_b64_tr_b16 v[198:199], v197 offset:0x400
	ds_read_b64_tr_b16 v[200:201], v197 offset:0xc00
	ds_read_b128 v[82:85], v188 offset:32768
	s_waitcnt lgkmcnt(7)
	v_mfma_f32_32x32x16_bf16 v[34:49], v[138:141], v[218:221], v[34:49]
	v_add_f32_e32 v242, v98, v242
	v_add_f32_e32 v242, v99, v242
	v_add_f32_e32 v242, v100, v242
	ds_read_b64_tr_b16 v[202:203], v197 offset:0x1400
	ds_read_b64_tr_b16 v[204:205], v197 offset:0x1c00
	s_waitcnt lgkmcnt(7)
	v_mfma_f32_32x32x16_bf16 v[34:49], v[134:137], v[222:225], v[34:49]
	v_add_f32_e32 v242, v101, v242
	v_add_f32_e32 v242, v102, v242
	v_add_f32_e32 v242, v103, v242
	ds_read_b64_tr_b16 v[206:207], v197 offset:0x2400
	ds_read_b64_tr_b16 v[208:209], v197 offset:0x2c00
	s_waitcnt lgkmcnt(7)
	v_mfma_f32_32x32x16_bf16 v[34:49], v[130:133], v[226:229], v[34:49]
	v_add_f32_e32 v242, v104, v242
	v_add_f32_e32 v242, v105, v242
	v_add_f32_e32 v242, v106, v242
	ds_read_b64_tr_b16 v[210:211], v197 offset:0x3400
	ds_read_b64_tr_b16 v[212:213], v197 offset:0x3c00
	s_waitcnt lgkmcnt(7)
	v_mfma_f32_32x32x16_bf16 v[18:33], v[142:145], v[198:201], v[18:33]
	v_add_f32_e32 v242, v107, v242
	v_add_f32_e32 v242, v108, v242
	v_add_f32_e32 v242, v109, v242
	ds_read_b64_tr_b16 v[214:215], v197 offset:0x600
	ds_read_b64_tr_b16 v[216:217], v197 offset:0xe00
	s_waitcnt lgkmcnt(6)
	v_mfma_f32_32x32x16_bf16 v[18:33], v[138:141], v[202:205], v[18:33]
	v_add_f32_e32 v242, v110, v242
	v_add_f32_e32 v242, v111, v242
	v_add_f32_e32 v242, v112, v242
	ds_read_b64_tr_b16 v[218:219], v197 offset:0x1600
	ds_read_b64_tr_b16 v[220:221], v197 offset:0x1e00
	s_waitcnt lgkmcnt(6)
	v_mfma_f32_32x32x16_bf16 v[18:33], v[134:137], v[206:209], v[18:33]
	v_add_f32_e32 v242, v113, v242
	v_mov_b32_e32 v243, v242
	s_nop 1
	ds_read_b64_tr_b16 v[222:223], v197 offset:0x2600
	ds_read_b64_tr_b16 v[224:225], v197 offset:0x2e00
	s_waitcnt lgkmcnt(6)
	v_mfma_f32_32x32x16_bf16 v[18:33], v[130:133], v[210:213], v[18:33]
	v_permlane32_swap_b32_e32 v242, v243
	v_add_f32_e32 v242, v242, v243
	v_fmac_f32_e32 v242, v184, v194
	v_mov_b32_e32 v184, v242
	ds_read_b64_tr_b16 v[226:227], v197 offset:0x3600
	ds_read_b64_tr_b16 v[228:229], v197 offset:0x3e00
	ds_read_b128 v[198:201], v190 offset:32768
	ds_read_b128 v[202:205], v190 offset:36864
	ds_read_b128 v[206:209], v191 offset:32768
	ds_read_b128 v[210:213], v191 offset:36864
	v_mfma_f32_32x32x16_bf16 v[98:113], v[82:85], v[126:129], v[66:81]
	v_mfma_f32_32x32x16_bf16 v[82:97], v[230:233], v[126:129], v[66:81]
	v_mfma_f32_32x32x16_bf16 v[98:113], v[234:237], v[122:125], v[98:113]
	v_mfma_f32_32x32x16_bf16 v[82:97], v[238:241], v[122:125], v[82:97]
	s_waitcnt lgkmcnt(3)
	v_mfma_f32_32x32x16_bf16 v[98:113], v[198:201], v[118:121], v[98:113]
	s_waitcnt lgkmcnt(2)
	v_mfma_f32_32x32x16_bf16 v[82:97], v[202:205], v[118:121], v[82:97]
	s_waitcnt lgkmcnt(1)
	v_mfma_f32_32x32x16_bf16 v[98:113], v[206:209], v[114:117], v[98:113]
	s_waitcnt lgkmcnt(0)
	v_mfma_f32_32x32x16_bf16 v[82:97], v[210:213], v[114:117], v[82:97]
	v_mfma_f32_32x32x16_bf16 v[2:17], v[142:145], v[214:217], v[2:17]
	v_mfma_f32_32x32x16_bf16 v[2:17], v[138:141], v[218:221], v[2:17]
	v_mfma_f32_32x32x16_bf16 v[2:17], v[134:137], v[222:225], v[2:17]
	v_mfma_f32_32x32x16_bf16 v[2:17], v[130:133], v[226:229], v[2:17]
	s_and_b64 vcc, exec, s[6:7]
	s_cbranch_vccnz .LBB0_614
	s_waitcnt vmcnt(1)

.LBB0_623:
	v_exp_f32_e32 v98, v98
	v_exp_f32_e32 v99, v99
	v_exp_f32_e32 v100, v100
	v_exp_f32_e32 v101, v101
	v_exp_f32_e32 v102, v102
	v_exp_f32_e32 v82, v82
	v_exp_f32_e32 v103, v103
	v_exp_f32_e32 v104, v104
	v_exp_f32_e32 v105, v105
	v_exp_f32_e32 v106, v106
	v_exp_f32_e32 v107, v107
	v_exp_f32_e32 v108, v108
	v_exp_f32_e32 v109, v109
	v_exp_f32_e32 v110, v110
	v_exp_f32_e32 v111, v111
	v_exp_f32_e32 v112, v112
	v_exp_f32_e32 v113, v113
	v_exp_f32_e32 v83, v83
	v_exp_f32_e32 v84, v84
	v_exp_f32_e32 v85, v85
	v_exp_f32_e32 v86, v86
	v_exp_f32_e32 v87, v87
	v_exp_f32_e32 v88, v88
	v_exp_f32_e32 v89, v89
	v_exp_f32_e32 v90, v90
	v_exp_f32_e32 v91, v91
	v_exp_f32_e32 v92, v92
	v_exp_f32_e32 v93, v93
	v_exp_f32_e32 v94, v94
	v_exp_f32_e32 v95, v95
	v_exp_f32_e32 v96, v96
	v_exp_f32_e32 v97, v97
	s_and_b64 vcc, exec, s[2:3]
	v_cvt_pk_bf16_f32 v142, v98, v99
	v_cvt_pk_bf16_f32 v143, v100, v101
	v_cvt_pk_bf16_f32 v144, v102, v103
	v_cvt_pk_bf16_f32 v145, v104, v105
	v_cvt_pk_bf16_f32 v138, v106, v107
	v_cvt_pk_bf16_f32 v139, v108, v109
	v_cvt_pk_bf16_f32 v140, v110, v111
	v_cvt_pk_bf16_f32 v141, v112, v113
	v_cvt_pk_bf16_f32 v134, v82, v83
	v_cvt_pk_bf16_f32 v135, v84, v85
	v_cvt_pk_bf16_f32 v136, v86, v87
	v_cvt_pk_bf16_f32 v137, v88, v89
	v_cvt_pk_bf16_f32 v130, v90, v91
	v_cvt_pk_bf16_f32 v131, v92, v93
	v_cvt_pk_bf16_f32 v132, v94, v95
	v_cvt_pk_bf16_f32 v133, v96, v97
	s_cbranch_vccnz .LBB0_625
	s_waitcnt vmcnt(1)
.LBB0_625:
	v_mov_b32_e32 v244, v197
	s_add_i32 s96, s96, 2
	s_and_b64 vcc, exec, s[0:1]
	s_cbranch_vccnz .Lrot_da_exit
	s_mov_b32 s0, s12
	s_mov_b32 s12, s75
	s_mov_b32 s75, s74
	s_mov_b32 s74, s0
	v_add_u32_e32 v238, s74, v193
	s_branch .LBB0_599
.Lrot_da_exit:
	s_barrier
	v_add_f32_e32 v242, v82, v83
	v_add_f32_e32 v242, v84, v242
	v_add_f32_e32 v242, v85, v242
	v_add_f32_e32 v242, v86, v242
	v_add_f32_e32 v242, v87, v242
	v_add_f32_e32 v242, v88, v242
	v_add_f32_e32 v242, v89, v242
	v_add_f32_e32 v242, v90, v242
	v_add_f32_e32 v242, v91, v242
	v_add_f32_e32 v242, v92, v242
	v_add_f32_e32 v242, v93, v242
	v_add_f32_e32 v242, v94, v242
	v_add_f32_e32 v242, v95, v242
	v_add_f32_e32 v242, v96, v242
	v_add_f32_e32 v242, v97, v242
	v_add_f32_e32 v242, v98, v242
	v_add_f32_e32 v242, v99, v242
	v_add_f32_e32 v242, v100, v242
	v_add_f32_e32 v242, v101, v242
	v_add_f32_e32 v242, v102, v242
	v_add_f32_e32 v242, v103, v242
	v_add_f32_e32 v242, v104, v242
	v_add_f32_e32 v242, v105, v242
	v_add_f32_e32 v242, v106, v242
	v_add_f32_e32 v242, v107, v242
	v_add_f32_e32 v242, v108, v242
	v_add_f32_e32 v242, v109, v242
	v_add_f32_e32 v242, v110, v242
	v_add_f32_e32 v242, v111, v242
	v_add_f32_e32 v242, v112, v242
	v_add_f32_e32 v242, v113, v242
	v_mov_b32_e32 v243, v242
	s_nop 1
	v_permlane32_swap_b32_e32 v242, v243
	v_add_f32_e32 v242, v242, v243
	v_fmac_f32_e32 v242, v184, v244
	v_mov_b32_e32 v184, v242
	s_branch .LBB0_629
